# phase 4 (gates + branch projections): XCD-affine item mapping, the 8 column tiles of a 128-row activation tile run on 8 consecutive workgroups of one XCD (j=q&7, mt=x+8*(q>>3)+64*round); tail hand-off
# speedup vs baseline: 1.0439x; 1.0107x over previous
.LBB0_765:
	s_or_b64 exec, exec, s[4:5]
	v_bfe_u32 v167, v153, 2, 4
	s_andn2_b64 vcc, exec, s[0:1]
	v_sub_u32_e32 v166, 0, v158
	v_lshlrev_b32_e32 v150, 10, v167
	s_waitcnt lgkmcnt(0)
	s_barrier
	s_cbranch_vccnz .LBB0_784
	v_readlane_b32 s64, v238, 0
	s_add_u32 s0, s30, 0x4920000
	v_readlane_b32 s66, v238, 2
	v_readlane_b32 s67, v238, 3
	s_addc_u32 s1, s31, 0
	s_mov_b64 s[6:7], s[66:67]
	s_waitcnt vmcnt(1)
	v_and_b32_e32 v3, 0x1c0, v162
	s_add_u32 s4, s6, 0x1000
	v_and_or_b32 v172, v155, 12, v3
	s_addc_u32 s5, s7, 0
	v_xor_b32_e32 v0, v153, v166
	v_and_b32_e32 v170, 0x4f, v153
	v_lshlrev_b32_e32 v173, 7, v172
	s_add_u32 s6, s30, 0x8ba0040
	v_lshlrev_b32_e32 v0, 3, v0
	v_or_b32_e32 v171, v3, v159
	v_or_b32_e32 v3, v173, v170
	s_addc_u32 s7, s31, 0
	s_lshl_b32 s10, s2, 7
	v_lshlrev_b32_e32 v169, 5, v154
	v_and_b32_e32 v1, 24, v0
	v_lshlrev_b32_e32 v182, 1, v3
	v_or_b32_e32 v3, s10, v167
	v_lshlrev_b32_e32 v178, 15, v154
	s_waitcnt vmcnt(0)
	v_and_b32_e32 v4, 48, v157
	v_add_u32_e32 v186, v3, v169
	v_or3_b32 v3, v178, v150, v1
	v_or_b32_e32 v175, v169, v167
	v_mov_b32_e32 v131, 0
	v_sub_u32_e32 v4, 0, v4
	v_lshlrev_b32_e32 v130, 1, v3
	v_or_b32_e32 v176, 16, v175
	v_lshlrev_b32_e32 v174, 4, v152
	v_bitop3_b32 v179, v153, 48, v4 bitop3:0x48
	v_lshl_add_u64 v[4:5], s[30:31], 0, v[130:131]
	v_or_b32_e32 v130, 0x8000, v130
	v_lshl_or_b32 v0, v175, 10, v1
	v_lshl_or_b32 v2, v176, 10, v1
	v_lshl_or_b32 v177, v154, 11, v174
	v_lshl_add_u64 v[132:133], v[4:5], 0, 64
	v_lshl_add_u64 v[4:5], s[30:31], 0, v[130:131]
	v_lshlrev_b32_e32 v3, 4, v159
	v_or_b32_e32 v168, s10, v158
	v_lshlrev_b32_e32 v180, 6, v171
	v_lshl_or_b32 v181, v170, 6, v179
	v_or_b32_e32 v183, 32, v182
	v_or_b32_e32 v184, 64, v182
	v_or_b32_e32 v185, 0x60, v182
	s_lshl_b32 s3, s84, 7
	v_or_b32_e32 v187, 16, v186
	v_lshl_add_u64 v[134:135], v[4:5], 0, 64
	v_lshl_or_b32 v151, v158, 8, v3
	v_mov_b32_e32 v188, 0x427f
	v_lshlrev_b32_e32 v189, 1, v1
	v_lshlrev_b32_e32 v190, 1, v0
	v_add_u32_e32 v191, 0x2000, v177
	v_add_u32_e32 v192, 0x4000, v177
	v_add_u32_e32 v193, 0x400, v177
	v_lshlrev_b32_e32 v194, 1, v2
	v_add_u32_e32 v195, 0x2400, v177
	v_add_u32_e32 v196, 0x4400, v177
	v_mov_b32_e32 v197, v168
	s_mov_b32 s11, s2
	s_cmp_eq_u32 s84, 0x200
	s_cbranch_scc0 .Lx5a_go
	s_and_b32 s8, s2, 7
	s_lshr_b32 s9, s2, 3
	s_and_b32 s12, s9, 7
	s_lshr_b32 s9, s9, 3
	s_mul_i32 s12, s12, 0x85
	s_lshl_b32 s9, s9, 3
	s_add_i32 s11, s12, s8
	s_add_i32 s11, s11, s9
	s_sub_i32 s8, s11, s2
	s_lshl_b32 s8, s8, 7
	v_add_u32_e32 v186, s8, v186
	v_add_u32_e32 v187, s8, v187
	v_add_u32_e32 v197, s8, v197
.Lx5a_go:
	v_readlane_b32 s65, v238, 1
	v_readlane_b32 s68, v238, 4
	v_readlane_b32 s69, v238, 5
	v_readlane_b32 s70, v238, 6
	v_readlane_b32 s71, v238, 7
	v_readlane_b32 s72, v238, 8
	v_readlane_b32 s73, v238, 9
	v_readlane_b32 s74, v238, 10
	v_readlane_b32 s75, v238, 11
	v_readlane_b32 s76, v238, 12
	v_readlane_b32 s77, v238, 13
	v_readlane_b32 s78, v238, 14
	v_readlane_b32 s79, v238, 15

.LBB0_770:
	s_nop 0
	v_add_u32_e32 v22, s8, v151
	ds_read_b128 v[18:21], v22
	ds_read_b128 v[22:25], v22 offset:32768
	v_ashrrev_i32_e32 v17, 31, v16
	v_lshlrev_b64 v[26:27], 10, v[16:17]
	v_lshl_add_u64 v[26:27], v[26:27], 0, v[108:109]
	s_waitcnt lgkmcnt(1)
	v_cvt_f32_f16_e32 v30, v18
	v_cvt_f32_f16_sdwa v31, v18 dst_sel:DWORD dst_unused:UNUSED_PAD src0_sel:WORD_1
	v_cvt_f32_f16_e32 v18, v19
	v_cvt_f32_f16_sdwa v19, v19 dst_sel:DWORD dst_unused:UNUSED_PAD src0_sel:WORD_1
	v_cvt_f32_f16_e32 v32, v20
	v_cvt_f32_f16_sdwa v33, v20 dst_sel:DWORD dst_unused:UNUSED_PAD src0_sel:WORD_1
	v_cvt_f32_f16_e32 v20, v21
	v_cvt_f32_f16_sdwa v21, v21 dst_sel:DWORD dst_unused:UNUSED_PAD src0_sel:WORD_1
	s_waitcnt lgkmcnt(0)
	v_cvt_f32_f16_e32 v34, v22
	v_cvt_f32_f16_sdwa v35, v22 dst_sel:DWORD dst_unused:UNUSED_PAD src0_sel:WORD_1
	v_cvt_f32_f16_e32 v22, v23
	v_cvt_f32_f16_sdwa v23, v23 dst_sel:DWORD dst_unused:UNUSED_PAD src0_sel:WORD_1
	v_cvt_f32_f16_e32 v36, v24
	v_cvt_f32_f16_sdwa v37, v24 dst_sel:DWORD dst_unused:UNUSED_PAD src0_sel:WORD_1
	v_cvt_f32_f16_e32 v24, v25
	v_cvt_f32_f16_sdwa v25, v25 dst_sel:DWORD dst_unused:UNUSED_PAD src0_sel:WORD_1
	v_pk_add_f32 v[18:19], v[6:7], v[18:19]
	v_pk_add_f32 v[30:31], v[4:5], v[30:31]
	v_pk_add_f32 v[20:21], v[2:3], v[20:21]
	v_pk_add_f32 v[32:33], v[0:1], v[32:33]
	v_pk_add_f32 v[22:23], v[14:15], v[22:23]
	v_pk_add_f32 v[34:35], v[12:13], v[34:35]
	v_pk_add_f32 v[24:25], v[10:11], v[24:25]
	v_pk_add_f32 v[36:37], v[8:9], v[36:37]
	v_mul_f32_e32 v17, 0xbfb8aa3b, v30
	v_mul_f32_e32 v30, 0xbfb8aa3b, v31
	v_mul_f32_e32 v18, 0xbfb8aa3b, v18
	v_mul_f32_e32 v19, 0xbfb8aa3b, v19
	v_mul_f32_e32 v31, 0xbfb8aa3b, v32
	v_mul_f32_e32 v32, 0xbfb8aa3b, v33
	v_mul_f32_e32 v20, 0xbfb8aa3b, v20
	v_mul_f32_e32 v21, 0xbfb8aa3b, v21
	v_mul_f32_e32 v33, 0xbfb8aa3b, v34
	v_mul_f32_e32 v34, 0xbfb8aa3b, v35
	v_mul_f32_e32 v22, 0xbfb8aa3b, v22
	v_mul_f32_e32 v23, 0xbfb8aa3b, v23
	v_mul_f32_e32 v35, 0xbfb8aa3b, v36
	v_mul_f32_e32 v36, 0xbfb8aa3b, v37
	v_mul_f32_e32 v24, 0xbfb8aa3b, v24
	v_mul_f32_e32 v25, 0xbfb8aa3b, v25
	v_exp_f32_e32 v17, v17
	v_exp_f32_e32 v30, v30
	v_exp_f32_e32 v18, v18
	v_exp_f32_e32 v19, v19
	v_exp_f32_e32 v31, v31
	v_exp_f32_e32 v32, v32
	v_exp_f32_e32 v20, v20
	v_exp_f32_e32 v21, v21
	v_exp_f32_e32 v33, v33
	v_exp_f32_e32 v34, v34
	v_exp_f32_e32 v22, v22
	v_exp_f32_e32 v23, v23
	v_exp_f32_e32 v35, v35
	v_exp_f32_e32 v36, v36
	v_exp_f32_e32 v24, v24
	v_exp_f32_e32 v25, v25
	v_add_f32_e32 v17, 1.0, v17
	v_add_f32_e32 v30, 1.0, v30
	v_add_f32_e32 v18, 1.0, v18
	v_add_f32_e32 v19, 1.0, v19
	v_add_f32_e32 v31, 1.0, v31
	v_add_f32_e32 v32, 1.0, v32
	v_add_f32_e32 v20, 1.0, v20
	v_add_f32_e32 v21, 1.0, v21
	v_add_f32_e32 v33, 1.0, v33
	v_add_f32_e32 v34, 1.0, v34
	v_add_f32_e32 v22, 1.0, v22
	v_add_f32_e32 v23, 1.0, v23
	v_add_f32_e32 v35, 1.0, v35
	v_add_f32_e32 v36, 1.0, v36
	v_add_f32_e32 v24, 1.0, v24
	v_add_f32_e32 v25, 1.0, v25
	v_rcp_f32_e32 v17, v17
	v_rcp_f32_e32 v30, v30
	v_rcp_f32_e32 v18, v18
	v_rcp_f32_e32 v19, v19
	v_rcp_f32_e32 v31, v31
	v_rcp_f32_e32 v32, v32
	v_rcp_f32_e32 v20, v20
	v_rcp_f32_e32 v21, v21
	v_rcp_f32_e32 v33, v33
	v_rcp_f32_e32 v34, v34
	v_rcp_f32_e32 v22, v22
	v_rcp_f32_e32 v23, v23
	v_rcp_f32_e32 v35, v35
	v_rcp_f32_e32 v36, v36
	v_rcp_f32_e32 v24, v24
	v_rcp_f32_e32 v25, v25
	s_addk_i32 s8, 0x1000
	v_lshlrev_b64 v[26:27], 1, v[26:27]
	v_add_u32_e32 v16, 16, v16
	s_cmpk_eq_u32 s8, 0x8000
	v_lshl_add_u64 v[28:29], s[60:61], 0, v[26:27]
	v_cvt_pk_f16_f32 v21, v20, v21
	v_cvt_pk_f16_f32 v20, v31, v32
	v_cvt_pk_f16_f32 v19, v18, v19
	v_cvt_pk_f16_f32 v18, v17, v30
	v_lshl_add_u64 v[26:27], s[0:1], 0, v[26:27]
	v_cvt_pk_f16_f32 v25, v24, v25
	v_cvt_pk_f16_f32 v24, v35, v36
	v_cvt_pk_f16_f32 v23, v22, v23
	v_cvt_pk_f16_f32 v22, v33, v34
	global_store_dwordx4 v[28:29], v[18:21], off
	global_store_dwordx4 v[26:27], v[22:25], off
	s_cbranch_scc0 .LBB0_770
	s_cmp_eq_u32 s84, 0x200
	s_cbranch_scc0 .Lx5a_orig
	s_add_i32 s11, s11, 64
	v_add_u32_e32 v186, 0x2000, v186
	v_add_u32_e32 v187, 0x2000, v187
	v_add_u32_e32 v197, 0x2000, v197
	s_lshr_b32 s8, s2, 3
	s_and_b32 s8, s8, 7
	s_mul_i32 s8, s8, 0x85
	s_addk_i32 s8, 0x85
	s_barrier
	s_cmp_ge_i32 s11, s8
	s_cbranch_scc0 .LBB0_767
	s_branch .Lx5a_done
.Lx5a_orig:
	s_add_i32 s11, s11, s84
	v_add_u32_e32 v186, s3, v186
	v_add_u32_e32 v187, s3, v187
	s_cmpk_gt_i32 s11, 0x427
	v_add_u32_e32 v197, s3, v197
	s_barrier
	s_cbranch_scc0 .LBB0_767
.Lx5a_done:
	v_lshrrev_b32_e32 v1, 3, v152
	v_or_b32_e32 v106, v169, v1
	v_or_b32_e32 v111, 24, v106
	v_lshrrev_b32_e32 v3, 1, v111
	v_lshrrev_b32_e32 v0, 1, v106
	v_or_b32_e32 v108, 8, v106
	v_xor_b32_e32 v3, v3, v153
	v_xor_b32_e32 v0, v0, v153
	v_lshrrev_b32_e32 v2, 1, v108
	v_lshlrev_b32_e32 v3, 3, v3
	v_lshlrev_b32_e32 v0, 3, v0
	v_xor_b32_e32 v2, v2, v153
	v_and_b32_e32 v112, 56, v3
	v_lshrrev_b32_e32 v3, 4, v152
	v_and_b32_e32 v107, 56, v0
	v_lshlrev_b32_e32 v2, 3, v2
	v_bitop3_b32 v5, v3, v162, 7 bitop3:0x78
	v_bitop3_b32 v3, v3, v129, 4 bitop3:0x36
	v_add3_u32 v120, v1, s10, v169
	v_lshl_add_u32 v1, v1, 10, v178
	v_and_b32_e32 v109, 56, v2
	v_mov_b32_e32 v65, 0
	v_lshlrev_b32_e32 v117, 4, v3
	v_lshlrev_b32_e32 v3, 1, v170
	v_add_lshl_u32 v64, v1, v107, 1
	v_lshlrev_b32_e32 v114, 4, v5
	v_lshl_or_b32 v118, v172, 8, v3
	v_lshl_add_u32 v119, v173, 1, v3
	s_mov_b64 s[6:7], 0x80
	v_lshl_add_u64 v[8:9], s[30:31], 0, v[64:65]
	v_add_u32_e32 v3, v1, v109
	v_mov_b32_e32 v5, 0x4000
	v_lshl_add_u64 v[66:67], v[8:9], 0, s[6:7]
	v_lshl_add_u32 v8, v3, 1, v5
	v_mov_b32_e32 v9, v65
	v_lshl_add_u64 v[8:9], s[30:31], 0, v[8:9]
	v_add_u32_e32 v64, 0x8000, v64
	v_add_u32_e32 v1, v1, v112
	v_mov_b32_e32 v3, 0xc000
	v_or_b32_e32 v110, 16, v106
	v_lshl_add_u64 v[68:69], v[8:9], 0, s[6:7]
	v_lshl_add_u64 v[8:9], s[30:31], 0, v[64:65]
	v_lshl_add_u32 v64, v1, 1, v3
	v_lshl_or_b32 v0, v106, 10, v107
	v_lshl_or_b32 v2, v108, 10, v109
	v_lshl_or_b32 v4, v110, 10, v107
	v_lshl_or_b32 v6, v111, 10, v112
	v_lshl_or_b32 v113, v154, 12, v174
	s_add_u32 s4, s30, 0x80
	v_lshl_add_u64 v[70:71], v[8:9], 0, s[6:7]
	v_lshl_add_u64 v[8:9], s[30:31], 0, v[64:65]
	v_lshlrev_b32_e32 v115, 7, v171
	v_lshlrev_b32_e32 v116, 7, v170
	s_addc_u32 s5, s31, 0
	v_add_u32_e32 v121, 8, v120
	v_add_u32_e32 v122, 16, v120
	v_add_u32_e32 v123, 24, v120
	v_lshl_add_u64 v[72:73], v[8:9], 0, s[6:7]
	v_mov_b32_e32 v124, 0x427f
	v_lshlrev_b32_e32 v125, 1, v107
	v_lshlrev_b32_e32 v126, 1, v109
	v_lshlrev_b32_e32 v127, 1, v112
	s_mov_b32 s10, 0xce20000
	s_mov_b32 s11, 0x10c0000
	v_lshlrev_b32_e32 v129, 1, v0
	v_add_u32_e32 v130, 0x4000, v113
	v_add_u32_e32 v131, 0x400, v113
	v_lshlrev_b32_e32 v132, 1, v2
	v_add_u32_e32 v133, 0x4400, v113
	v_add_u32_e32 v134, 0x800, v113
	v_lshlrev_b32_e32 v135, 1, v4
	v_add_u32_e32 v136, 0x4800, v113
	v_add_u32_e32 v137, 0xc00, v113
	v_lshlrev_b32_e32 v138, 1, v6
	v_add_u32_e32 v139, 0x4c00, v113
	s_mov_b32 s20, s2
	s_cmp_eq_u32 s84, 0x200
	s_cbranch_scc0 .Lp5_nosig
	s_and_b32 s8, s2, 7
	s_lshr_b32 s9, s2, 3
	s_and_b32 s12, s9, 7
	s_lshr_b32 s9, s9, 3
	s_mul_i32 s12, s12, 0x85
	s_lshl_b32 s9, s9, 3
	s_add_i32 s20, s12, s8
	s_add_i32 s20, s20, s9
	s_sub_i32 s9, s20, s2
	s_lshl_b32 s9, s9, 7
	v_add_u32_e32 v120, s9, v120
	v_add_u32_e32 v121, s9, v121
	v_add_u32_e32 v122, s9, v122
	v_add_u32_e32 v123, s9, v123
	v_add_u32_e32 v168, s9, v168
	s_cmp_lt_u32 s2, 64
	s_cbranch_scc0 .Lp5_nosig
	s_cmp_lt_u32 s8, 5
	s_cbranch_scc0 .Lp5_nosig
	s_waitcnt vmcnt(0) lgkmcnt(0)
	s_barrier
	s_and_saveexec_b64 s[6:7], s[82:83]
	s_cbranch_execz .Lp5_sigdone
	buffer_wbl2 sc1
	s_waitcnt vmcnt(0)
	s_add_u32 s8, s30, 0xf9c4000
	s_addc_u32 s9, s31, 0
	s_lshl_b32 s12, s2, 2
	v_mov_b32_e32 v0, s12
	v_mov_b32_e32 v1, 1
	global_store_dword v0, v1, s[8:9] sc0 sc1
	s_waitcnt vmcnt(0)

.LBB0_781:
	v_or_b32_e32 v0, s6, v128
	v_ashrrev_i32_e32 v1, 31, v0
	v_subrev_u32_e32 v2, s24, v168
	s_mov_b32 s6, 0
	s_waitcnt lgkmcnt(0)
	s_barrier
	s_cmp_eq_u32 s84, 0x200
	s_cbranch_scc0 .Lp5_nowait
	s_lshr_b32 s7, s2, 6
	s_cmp_eq_u32 s7, 1
	s_cbranch_scc0 .Lp5_nowait
	s_lshr_b32 s7, s2, 3
	s_and_b32 s7, s7, 7
	s_mul_i32 s7, s7, 0x85
	s_and_b32 s8, s2, 7
	s_add_i32 s7, s7, s8
	s_addk_i32 s7, 0x80
	s_cmp_eq_u32 s20, s7
	s_cbranch_scc0 .Lp5_nowait
	s_sub_i32 s7, s2, 64
	s_lshl_b32 s7, s7, 2
	s_add_u32 s8, s30, 0xf9c4000
	s_addc_u32 s9, s31, 0
	s_and_saveexec_b64 s[12:13], s[82:83]
	s_cbranch_execz .Lp5_got
	v_mov_b32_e32 v3, s7

.Lp5_nowait:
.LBB0_782:
	v_ashrrev_i32_e32 v3, 31, v2
	v_lshlrev_b64 v[4:5], 10, v[2:3]
	v_lshl_add_u64 v[4:5], v[4:5], 0, v[0:1]
	v_lshlrev_b64 v[4:5], 1, v[4:5]
	v_lshl_add_u64 v[12:13], s[0:1], 0, v[4:5]
	v_lshl_add_u64 v[20:21], s[60:61], 0, v[4:5]
	global_load_dwordx4 v[4:7], v[12:13], off
	global_load_dwordx4 v[8:11], v[20:21], off
	v_add_u32_e32 v3, s6, v151
	ds_read_b128 v[12:15], v3 offset:32768
	ds_read_b128 v[16:19], v3
	s_addk_i32 s6, 0x1000
	v_add_u32_e32 v2, 16, v2
	s_cmpk_eq_u32 s6, 0x8000
	s_waitcnt vmcnt(1) lgkmcnt(1)
	v_pk_mul_f16 v3, v12, v4
	v_pk_mul_f16 v4, v13, v5
	v_pk_mul_f16 v5, v14, v6
	v_pk_mul_f16 v6, v15, v7
	s_waitcnt vmcnt(0) lgkmcnt(0)
	v_pk_fma_f16 v7, v19, v11, v6
	v_pk_fma_f16 v6, v18, v10, v5
	v_pk_fma_f16 v5, v17, v9, v4
	v_pk_fma_f16 v4, v16, v8, v3
	global_store_dwordx4 v[20:21], v[4:7], off
	s_cbranch_scc0 .LBB0_782
	s_cmp_eq_u32 s84, 0x200
	s_cbranch_scc0 .Lp5_orig
	s_barrier
	s_lshr_b32 s6, s2, 3
	s_and_b32 s6, s6, 7
	s_mul_i32 s6, s6, 0x85
	s_and_b32 s7, s2, 7
	s_add_i32 s8, s6, s7
	s_addk_i32 s8, 0x80
	s_cmp_eq_u32 s20, s8
	s_cbranch_scc1 .LBB0_784
	s_add_i32 s20, s20, 64
	v_add_u32_e32 v120, 0x2000, v120
	v_add_u32_e32 v121, 0x2000, v121
	v_add_u32_e32 v122, 0x2000, v122
	v_add_u32_e32 v123, 0x2000, v123
	v_add_u32_e32 v168, 0x2000, v168
	s_add_i32 s9, s6, 0x85
	s_cmp_lt_i32 s20, s9
	s_cbranch_scc0 .Lp5_xend
	s_cmp_eq_u32 s20, s8
	s_cbranch_scc0 .LBB0_773
	s_branch .LBB0_784
.Lp5_xend:
	s_lshr_b32 s9, s2, 6
	s_cmp_eq_u32 s9, 1
	s_cbranch_scc0 .LBB0_784
	s_cmp_lt_u32 s7, 5
	s_cbranch_scc0 .LBB0_784
	s_mov_b32 s20, s8
	v_add_u32_e32 v120, 0xfffffc00, v120
	v_add_u32_e32 v121, 0xfffffc00, v121
	v_add_u32_e32 v122, 0xfffffc00, v122
	v_add_u32_e32 v123, 0xfffffc00, v123
	v_add_u32_e32 v168, 0xfffffc00, v168
	s_branch .LBB0_773
.Lp5_orig:
	s_add_i32 s20, s20, s84
	v_add_u32_e32 v120, s3, v120
	v_add_u32_e32 v121, s3, v121
	v_add_u32_e32 v122, s3, v122
	v_add_u32_e32 v123, s3, v123
	v_add_u32_e32 v168, s3, v168
	s_barrier
	s_cmpk_gt_i32 s20, 0x427
	s_cbranch_scc0 .LBB0_773
